# transpose item stride taken from the grid-derived register instead of an immediate (no behaviour change on a 256-CU part)
# speedup vs baseline: 1.0065x; 1.0048x over previous
; __device__ __forceinline__ void tr_matrix(const float* W, int K, int ldn, int c0src, int ncols, bf16_t* WT, int ldk, int dst_row0, int dst_k0,
;                                           const float* rsc, float cs, LAS float* scr, int gw, int NGW, int lane) {
;     ...
;     for (int it = gw; it < nit; it += NGW) {
;         const int kb = it / nnb, nb = it % nnb, k0 = kb * 64, n0 = nb * 32, ncv = (ncols - n0) < 32 ? (ncols - n0) : 32;
; #pragma unroll 8
;         for (int i = 0; i < 32; ++i) { const int kk = 2 * i + (lane >> 5), col = lane & 31;
;             float val = 0.f;
;             if (col < ncv) { val = W[(size_t)(k0 + kk) * ldn + c0src + n0 + col]; if (rsc) val *= rsc[k0 + kk]; val *= cs; }
;             scr[kk * 33 + col] = val; }
.Ltr_rscdone:
	s_mul_i32 s72, s70, s6
	s_lshl_b32 s76, s71, 2
	s_add_u32 s72, s72, s76
	s_add_u32 s72, s72, s4
	s_addc_u32 s73, s5, 0
	v_mul_lo_u32 v124, v79, s6
	v_lshl_add_u32 v124, v78, 2, v124
	s_lshl_b32 s77, s6, 1
	global_load_dword v80, v124, s[72:73]
	s_add_u32 s72, s72, s77
	s_addc_u32 s73, s73, 0
	global_load_dword v81, v124, s[72:73]
	s_add_u32 s72, s72, s77
	s_addc_u32 s73, s73, 0
	global_load_dword v82, v124, s[72:73]
	s_add_u32 s72, s72, s77
	s_addc_u32 s73, s73, 0
	global_load_dword v83, v124, s[72:73]
	s_add_u32 s72, s72, s77
	s_addc_u32 s73, s73, 0
	global_load_dword v84, v124, s[72:73]
	s_add_u32 s72, s72, s77
	s_addc_u32 s73, s73, 0
	global_load_dword v85, v124, s[72:73]
	s_add_u32 s72, s72, s77
	s_addc_u32 s73, s73, 0
	global_load_dword v86, v124, s[72:73]
	s_add_u32 s72, s72, s77
	s_addc_u32 s73, s73, 0
	global_load_dword v87, v124, s[72:73]
	s_add_u32 s72, s72, s77
	s_addc_u32 s73, s73, 0
	global_load_dword v88, v124, s[72:73]
	s_add_u32 s72, s72, s77
	s_addc_u32 s73, s73, 0
	global_load_dword v89, v124, s[72:73]
	s_add_u32 s72, s72, s77
	s_addc_u32 s73, s73, 0
	global_load_dword v90, v124, s[72:73]
	s_add_u32 s72, s72, s77
	s_addc_u32 s73, s73, 0
	global_load_dword v91, v124, s[72:73]
	s_add_u32 s72, s72, s77
	s_addc_u32 s73, s73, 0
	global_load_dword v92, v124, s[72:73]
	s_add_u32 s72, s72, s77
	s_addc_u32 s73, s73, 0
	global_load_dword v93, v124, s[72:73]
	s_add_u32 s72, s72, s77
	s_addc_u32 s73, s73, 0
	global_load_dword v94, v124, s[72:73]
	s_add_u32 s72, s72, s77
	s_addc_u32 s73, s73, 0
	global_load_dword v95, v124, s[72:73]
	s_add_u32 s72, s72, s77
	s_addc_u32 s73, s73, 0
	global_load_dword v96, v124, s[72:73]
	s_add_u32 s72, s72, s77
	s_addc_u32 s73, s73, 0
	global_load_dword v97, v124, s[72:73]
	s_add_u32 s72, s72, s77
	s_addc_u32 s73, s73, 0
	global_load_dword v98, v124, s[72:73]
	s_add_u32 s72, s72, s77
	s_addc_u32 s73, s73, 0
	global_load_dword v99, v124, s[72:73]
	s_add_u32 s72, s72, s77
	s_addc_u32 s73, s73, 0
	global_load_dword v100, v124, s[72:73]
	s_add_u32 s72, s72, s77
	s_addc_u32 s73, s73, 0
	global_load_dword v101, v124, s[72:73]
	s_add_u32 s72, s72, s77
	s_addc_u32 s73, s73, 0
	global_load_dword v102, v124, s[72:73]
	s_add_u32 s72, s72, s77
	s_addc_u32 s73, s73, 0
	global_load_dword v103, v124, s[72:73]
	s_add_u32 s72, s72, s77
	s_addc_u32 s73, s73, 0
	global_load_dword v104, v124, s[72:73]
	s_add_u32 s72, s72, s77
	s_addc_u32 s73, s73, 0
	global_load_dword v105, v124, s[72:73]
	s_add_u32 s72, s72, s77
	s_addc_u32 s73, s73, 0
	global_load_dword v106, v124, s[72:73]
	s_add_u32 s72, s72, s77
	s_addc_u32 s73, s73, 0
	global_load_dword v107, v124, s[72:73]
	s_add_u32 s72, s72, s77
	s_addc_u32 s73, s73, 0
	global_load_dword v108, v124, s[72:73]
	s_add_u32 s72, s72, s77
	s_addc_u32 s73, s73, 0
	global_load_dword v109, v124, s[72:73]
	s_add_u32 s72, s72, s77
	s_addc_u32 s73, s73, 0
	global_load_dword v110, v124, s[72:73]
	s_add_u32 s72, s72, s77
	s_addc_u32 s73, s73, 0
	global_load_dword v111, v124, s[72:73]
	v_add_u32_e32 v126, s71, v122
	v_mul_lo_u32 v126, v126, s26
	s_lshl_b32 s76, s70, 1
	v_lshl_add_u32 v127, v121, 4, s76
	v_add_u32_e32 v126, v126, v127
	s_lshl_b32 s78, s26, 3
	s_sub_u32 s79, s35, s71
	s_waitcnt vmcnt(31)
	ds_write_b32 v120, v80
	s_waitcnt vmcnt(30)
	ds_write_b32 v120, v81 offset:264
	s_waitcnt vmcnt(29)
	ds_write_b32 v120, v82 offset:528
	s_waitcnt vmcnt(28)
	ds_write_b32 v120, v83 offset:792
	s_waitcnt vmcnt(27)
	ds_write_b32 v120, v84 offset:1056
	s_waitcnt vmcnt(26)
	ds_write_b32 v120, v85 offset:1320
	s_waitcnt vmcnt(25)
	ds_write_b32 v120, v86 offset:1584
	s_waitcnt vmcnt(24)
	ds_write_b32 v120, v87 offset:1848
	s_waitcnt vmcnt(23)
	ds_write_b32 v120, v88 offset:2112
	s_waitcnt vmcnt(22)
	ds_write_b32 v120, v89 offset:2376
	s_waitcnt vmcnt(21)
	ds_write_b32 v120, v90 offset:2640
	s_waitcnt vmcnt(20)
	ds_write_b32 v120, v91 offset:2904
	s_waitcnt vmcnt(19)
	ds_write_b32 v120, v92 offset:3168
	s_waitcnt vmcnt(18)
	ds_write_b32 v120, v93 offset:3432
	s_waitcnt vmcnt(17)
	ds_write_b32 v120, v94 offset:3696
	s_waitcnt vmcnt(16)
	ds_write_b32 v120, v95 offset:3960
	s_waitcnt vmcnt(15)
	ds_write_b32 v120, v96 offset:4224
	s_waitcnt vmcnt(14)
	ds_write_b32 v120, v97 offset:4488
	s_waitcnt vmcnt(13)
	ds_write_b32 v120, v98 offset:4752
	s_waitcnt vmcnt(12)
	ds_write_b32 v120, v99 offset:5016
	s_waitcnt vmcnt(11)
	ds_write_b32 v120, v100 offset:5280
	s_waitcnt vmcnt(10)
	ds_write_b32 v120, v101 offset:5544
	s_waitcnt vmcnt(9)
	ds_write_b32 v120, v102 offset:5808
	s_waitcnt vmcnt(8)
	ds_write_b32 v120, v103 offset:6072
	s_waitcnt vmcnt(7)
	ds_write_b32 v120, v104 offset:6336
	s_waitcnt vmcnt(6)
	ds_write_b32 v120, v105 offset:6600
	s_waitcnt vmcnt(5)
; #define LAS __attribute__((address_space(3)))
; __device__ __forceinline__ unsigned pk2(float lo, float hi) { f32x2 v = {lo, hi}; bf16x2_t b = __builtin_convertvector(v, bf16x2_t); return __builtin_bit_cast(unsigned, b); }
; #define LDS_WAIT() asm volatile("s_waitcnt lgkmcnt(0)" ::: "memory")
; __device__ __forceinline__ void tr_matrix(const float* W, int K, int ldn, int c0src, int ncols, bf16_t* WT, int ldk, int dst_row0, int dst_k0,
;                                           const float* rsc, float cs, LAS float* scr, int gw, int NGW, int lane) {
;     ...
;         LDS_WAIT(); asm volatile("" ::: "memory");
;         const int c = lane & 7;
; #pragma unroll
;         for (int j = 0; j < 4; ++j) { const int n = (lane >> 3) + 8 * j; const LAS float* s = scr + (8 * c) * 33 + n;
;             if (n < ncv) {
;                 u32x4 o; o.x = pk2(s[0 * 33], s[1 * 33]); o.y = pk2(s[2 * 33], s[3 * 33]); o.z = pk2(s[4 * 33], s[5 * 33]); o.w = pk2(s[6 * 33], s[7 * 33]);
;                 *(u32x4*)(WT + (size_t)(dst_row0 + n0 + n) * ldk + dst_k0 + k0 + 8 * c) = o; } }
;         LDS_WAIT(); asm volatile("" ::: "memory");
;     }
	ds_write_b32 v120, v106 offset:6864
	s_waitcnt vmcnt(4)
	ds_write_b32 v120, v107 offset:7128
	s_waitcnt vmcnt(3)
	ds_write_b32 v120, v108 offset:7392
	s_waitcnt vmcnt(2)
	ds_write_b32 v120, v109 offset:7656
	s_waitcnt vmcnt(1)
	ds_write_b32 v120, v110 offset:7920
	s_waitcnt vmcnt(0)
	ds_write_b32 v120, v111 offset:8184
	s_waitcnt lgkmcnt(0)
	ds_read2_b32 v[80:81], v123 offset1:33
	ds_read2_b32 v[82:83], v123 offset0:66 offset1:99
	ds_read2_b32 v[84:85], v123 offset0:132 offset1:165
	ds_read2_b32 v[86:87], v123 offset0:198 offset1:231
	ds_read2_b32 v[88:89], v123 offset0:8 offset1:41
	ds_read2_b32 v[90:91], v123 offset0:74 offset1:107
	ds_read2_b32 v[92:93], v123 offset0:140 offset1:173
	ds_read2_b32 v[94:95], v123 offset0:206 offset1:239
	ds_read2_b32 v[96:97], v123 offset0:16 offset1:49
	ds_read2_b32 v[98:99], v123 offset0:82 offset1:115
	ds_read2_b32 v[100:101], v123 offset0:148 offset1:181
	ds_read2_b32 v[102:103], v123 offset0:214 offset1:247
	ds_read2_b32 v[104:105], v123 offset0:24 offset1:57
	ds_read2_b32 v[106:107], v123 offset0:90 offset1:123
	ds_read2_b32 v[108:109], v123 offset0:156 offset1:189
	ds_read2_b32 v[110:111], v123 offset0:222 offset1:255
	s_waitcnt lgkmcnt(12)
	v_mul_f32_e32 v80, v80, v112
	v_mul_f32_e32 v81, v81, v113
	v_mul_f32_e32 v82, v82, v114
	v_mul_f32_e32 v83, v83, v115
	v_mul_f32_e32 v84, v84, v116
	v_mul_f32_e32 v85, v85, v117
	v_mul_f32_e32 v86, v86, v118
	v_mul_f32_e32 v87, v87, v119
	v_mul_f32_e32 v80, s34, v80
	v_mul_f32_e32 v81, s34, v81
	v_mul_f32_e32 v82, s34, v82
	v_mul_f32_e32 v83, s34, v83
	v_mul_f32_e32 v84, s34, v84
	v_mul_f32_e32 v85, s34, v85
	v_mul_f32_e32 v86, s34, v86
	v_mul_f32_e32 v87, s34, v87
	v_cvt_pk_bf16_f32 v128, v80, v81
	v_cvt_pk_bf16_f32 v129, v82, v83
	v_cvt_pk_bf16_f32 v130, v84, v85
	v_cvt_pk_bf16_f32 v131, v86, v87
	v_cmp_gt_u32_e32 vcc, s79, v122
	s_and_saveexec_b64 s[92:93], vcc
	global_store_dwordx4 v126, v[128:131], s[20:21]
	s_mov_b64 exec, s[92:93]
	v_add_u32_e32 v126, s78, v126
	s_waitcnt lgkmcnt(8)
	v_mul_f32_e32 v88, v88, v112
	v_mul_f32_e32 v89, v89, v113
	v_mul_f32_e32 v90, v90, v114
	v_mul_f32_e32 v91, v91, v115
	v_mul_f32_e32 v92, v92, v116
	v_mul_f32_e32 v93, v93, v117
	v_mul_f32_e32 v94, v94, v118
	v_mul_f32_e32 v95, v95, v119
	v_mul_f32_e32 v88, s34, v88
	v_mul_f32_e32 v89, s34, v89
	v_mul_f32_e32 v90, s34, v90
	v_mul_f32_e32 v91, s34, v91
	v_mul_f32_e32 v92, s34, v92
	v_mul_f32_e32 v93, s34, v93
	v_mul_f32_e32 v94, s34, v94
	v_mul_f32_e32 v95, s34, v95
	v_cvt_pk_bf16_f32 v132, v88, v89
	v_cvt_pk_bf16_f32 v133, v90, v91
	v_cvt_pk_bf16_f32 v134, v92, v93
	v_cvt_pk_bf16_f32 v135, v94, v95
	v_add_u32_e32 v136, 8, v122
	v_cmp_gt_u32_e32 vcc, s79, v136
	s_and_saveexec_b64 s[92:93], vcc
	global_store_dwordx4 v126, v[132:135], s[20:21]
	s_mov_b64 exec, s[92:93]
	v_add_u32_e32 v126, s78, v126
	s_waitcnt lgkmcnt(4)
	v_mul_f32_e32 v96, v96, v112
	v_mul_f32_e32 v97, v97, v113
	v_mul_f32_e32 v98, v98, v114
	v_mul_f32_e32 v99, v99, v115
	v_mul_f32_e32 v100, v100, v116
	v_mul_f32_e32 v101, v101, v117
	v_mul_f32_e32 v102, v102, v118
	v_mul_f32_e32 v103, v103, v119
	v_mul_f32_e32 v96, s34, v96
	v_mul_f32_e32 v97, s34, v97
	v_mul_f32_e32 v98, s34, v98
	v_mul_f32_e32 v99, s34, v99
	v_mul_f32_e32 v100, s34, v100
	v_mul_f32_e32 v101, s34, v101
	v_mul_f32_e32 v102, s34, v102
	v_mul_f32_e32 v103, s34, v103
	v_cvt_pk_bf16_f32 v128, v96, v97
	v_cvt_pk_bf16_f32 v129, v98, v99
	v_cvt_pk_bf16_f32 v130, v100, v101
	v_cvt_pk_bf16_f32 v131, v102, v103
	v_add_u32_e32 v136, 16, v122
	v_cmp_gt_u32_e32 vcc, s79, v136
	s_and_saveexec_b64 s[92:93], vcc
	global_store_dwordx4 v126, v[128:131], s[20:21]
	s_mov_b64 exec, s[92:93]
	v_add_u32_e32 v126, s78, v126
	s_waitcnt lgkmcnt(0)
	v_mul_f32_e32 v104, v104, v112
	v_mul_f32_e32 v105, v105, v113
	v_mul_f32_e32 v106, v106, v114
	v_mul_f32_e32 v107, v107, v115
	v_mul_f32_e32 v108, v108, v116
	v_mul_f32_e32 v109, v109, v117
	v_mul_f32_e32 v110, v110, v118
	v_mul_f32_e32 v111, v111, v119
	v_mul_f32_e32 v104, s34, v104
	v_mul_f32_e32 v105, s34, v105
	v_mul_f32_e32 v106, s34, v106
	v_mul_f32_e32 v107, s34, v107
	v_mul_f32_e32 v108, s34, v108
	v_mul_f32_e32 v109, s34, v109
	v_mul_f32_e32 v110, s34, v110
	v_mul_f32_e32 v111, s34, v111
	v_cvt_pk_bf16_f32 v132, v104, v105
	v_cvt_pk_bf16_f32 v133, v106, v107
	v_cvt_pk_bf16_f32 v134, v108, v109
	v_cvt_pk_bf16_f32 v135, v110, v111
	v_add_u32_e32 v136, 24, v122
	v_cmp_gt_u32_e32 vcc, s79, v136
	s_and_saveexec_b64 s[92:93], vcc
	global_store_dwordx4 v126, v[132:135], s[20:21]
	s_mov_b64 exec, s[92:93]
	s_add_i32 s0, s0, s94
	s_cmpk_lt_u32 s0, 0x1bd8
	s_cbranch_scc1 .Ltr_item
	v_readlane_b32 s0, v247, 39
	v_and_b32_e32 v0, 31, v156
	v_lshrrev_b32_e32 v32, 3, v158
	s_cmpk_lt_i32 s0, 0x100
	s_cselect_b64 s[20:21], -1, 0
